# v_rm_m1 + X4, A4 and M2 epilogues read the residual tile via coalesced LDS-DMA + ds_read
# baseline (speedup 1.0000x reference)
.LBB0_1027:
	v_lshl_add_u32 v198, s78, 8, v5
	v_lshl_or_b32 v200, s79, 8, v242
	s_barrier
	v_readfirstlane_b32 s30, v0
	v_and_b32_e32 v107, 63, v0
	v_lshrrev_b32_e32 v108, 3, v107
	v_and_b32_e32 v106, -16, v198
	v_add_u32_e32 v106, v106, v108
	v_lshlrev_b32_e32 v106, 11, v106
	v_and_b32_e32 v109, 7, v107
	v_xor_b32_e32 v109, v109, v108
	v_lshl_add_u32 v106, v109, 4, v106
	v_lshrrev_b32_e32 v109, 5, v200
	v_lshl_add_u32 v106, v109, 6, v106
	s_lshr_b32 s30, s30, 6
	s_lshl_b32 s30, s30, 14
	v_and_b32_e32 v109, 7, v107
	v_lshrrev_b32_e32 v108, 4, v107
	v_xor_b32_e32 v108, v108, v109
	v_lshlrev_b32_e32 v108, 4, v108
	v_lshl_add_u32 v108, v109, 7, v108
	v_bfe_u32 v109, v107, 3, 1
	v_lshl_add_u32 v108, v109, 10, v108
	v_add_u32_e32 v107, s30, v108
	v_xor_b32_e32 v108, 64, v107
	v_ashrrev_i32_e32 v201, 31, v200
	v_ashrrev_i32_e32 v199, 31, v198
	v_lshl_add_u64 v[202:203], v[200:201], 1, s[16:17]
	v_lshlrev_b64 v[90:91], 11, v[198:199]
	v_or_b32_e32 v228, 16, v198
	v_lshl_add_u64 v[90:91], v[202:203], 0, v[90:91]
	v_ashrrev_i32_e32 v229, 31, v228
	s_add_i32 m0, s30, 0x0
	s_add_u32 s34, s16, 0x0
	s_addc_u32 s35, s17, 0
	global_load_lds_dwordx4 v106, s[34:35]
	s_add_i32 m0, s30, 0x400
	s_add_u32 s34, s16, 0x4000
	s_addc_u32 s35, s17, 0
	global_load_lds_dwordx4 v106, s[34:35]
	v_lshlrev_b64 v[90:91], 11, v[228:229]
	v_or_b32_e32 v226, 32, v198
	v_lshl_add_u64 v[90:91], v[202:203], 0, v[90:91]
	v_ashrrev_i32_e32 v227, 31, v226
	s_add_i32 m0, s30, 0x800
	s_add_u32 s34, s16, 0x8000
	s_addc_u32 s35, s17, 0
	global_load_lds_dwordx4 v106, s[34:35]
	s_add_i32 m0, s30, 0xc00
	s_add_u32 s34, s16, 0xc000
	s_addc_u32 s35, s17, 0
	global_load_lds_dwordx4 v106, s[34:35]
	v_lshlrev_b64 v[90:91], 11, v[226:227]
	v_or_b32_e32 v212, 48, v198
	v_lshl_add_u64 v[90:91], v[202:203], 0, v[90:91]
	v_ashrrev_i32_e32 v213, 31, v212
	s_add_i32 m0, s30, 0x1000
	s_add_u32 s34, s16, 0x10000
	s_addc_u32 s35, s17, 0
	global_load_lds_dwordx4 v106, s[34:35]
	s_add_i32 m0, s30, 0x1400
	s_add_u32 s34, s16, 0x14000
	s_addc_u32 s35, s17, 0
	global_load_lds_dwordx4 v106, s[34:35]
	v_lshlrev_b64 v[90:91], 11, v[212:213]
	v_add_u32_e32 v210, 0x80, v198
	v_lshl_add_u64 v[90:91], v[202:203], 0, v[90:91]
	v_ashrrev_i32_e32 v211, 31, v210
	s_add_i32 m0, s30, 0x1800
	s_add_u32 s34, s16, 0x18000
	s_addc_u32 s35, s17, 0
	global_load_lds_dwordx4 v106, s[34:35]
	s_add_i32 m0, s30, 0x1c00
	s_add_u32 s34, s16, 0x1c000
	s_addc_u32 s35, s17, 0
	global_load_lds_dwordx4 v106, s[34:35]
	v_lshlrev_b64 v[90:91], 11, v[210:211]
	v_add_u32_e32 v208, 0x90, v198
	v_lshl_add_u64 v[90:91], v[202:203], 0, v[90:91]
	v_ashrrev_i32_e32 v209, 31, v208
	s_add_i32 m0, s30, 0x2000
	s_add_u32 s34, s16, 0x40000
	s_addc_u32 s35, s17, 0
	global_load_lds_dwordx4 v106, s[34:35]
	s_add_i32 m0, s30, 0x2400
	s_add_u32 s34, s16, 0x44000
	s_addc_u32 s35, s17, 0
	global_load_lds_dwordx4 v106, s[34:35]
	v_lshlrev_b64 v[90:91], 11, v[208:209]
	v_add_u32_e32 v206, 0xa0, v198
	v_lshl_add_u64 v[90:91], v[202:203], 0, v[90:91]
	v_ashrrev_i32_e32 v207, 31, v206
	s_add_i32 m0, s30, 0x2800
	s_add_u32 s34, s16, 0x48000
	s_addc_u32 s35, s17, 0
	global_load_lds_dwordx4 v106, s[34:35]
	s_add_i32 m0, s30, 0x2c00
	s_add_u32 s34, s16, 0x4c000
	s_addc_u32 s35, s17, 0
	global_load_lds_dwordx4 v106, s[34:35]
	v_lshlrev_b64 v[90:91], 11, v[206:207]
	v_add_u32_e32 v204, 0xb0, v198
	v_lshl_add_u64 v[90:91], v[202:203], 0, v[90:91]
	v_ashrrev_i32_e32 v205, 31, v204
	s_add_i32 m0, s30, 0x3000
	s_add_u32 s34, s16, 0x50000
	s_addc_u32 s35, s17, 0
	global_load_lds_dwordx4 v106, s[34:35]
	s_add_i32 m0, s30, 0x3400
	s_add_u32 s34, s16, 0x54000
	s_addc_u32 s35, s17, 0
	global_load_lds_dwordx4 v106, s[34:35]
	v_lshlrev_b64 v[90:91], 11, v[204:205]
	v_lshl_add_u64 v[90:91], v[202:203], 0, v[90:91]
	s_add_i32 m0, s30, 0x3800
	s_add_u32 s34, s16, 0x58000
	s_addc_u32 s35, s17, 0
	global_load_lds_dwordx4 v106, s[34:35]
	s_nop 0
	s_add_i32 m0, s30, 0x3c00
	s_add_u32 s34, s16, 0x5c000
	s_addc_u32 s35, s17, 0
	global_load_lds_dwordx4 v106, s[34:35]
	v_cndmask_b32_e64 v230, 0, 1, s[24:25]
	v_cmp_ne_u32_e64 s[6:7], 1, v230
	v_lshlrev_b64 v[230:231], 10, v[198:199]
	v_lshl_add_u64 v[232:233], v[230:231], 0, v[200:201]
	s_mov_b64 s[8:9], -1
	s_andn2_b64 vcc, exec, s[24:25]
	s_waitcnt vmcnt(0)
	ds_read_b128 v[194:197], v107 offset:0
	ds_read_b128 v[190:193], v108 offset:0
	ds_read_b128 v[186:189], v107 offset:2048
	ds_read_b128 v[182:185], v108 offset:2048
	ds_read_b128 v[178:181], v107 offset:4096
	ds_read_b128 v[174:177], v108 offset:4096
	ds_read_b128 v[170:173], v107 offset:6144
	ds_read_b128 v[166:169], v108 offset:6144
	ds_read_b128 v[162:165], v107 offset:8192
	ds_read_b128 v[158:161], v108 offset:8192
	ds_read_b128 v[146:149], v107 offset:10240
	ds_read_b128 v[134:137], v108 offset:10240
	ds_read_b128 v[126:129], v107 offset:12288
	ds_read_b128 v[114:117], v108 offset:12288
	ds_read_b128 v[90:93], v108 offset:14336
	ds_read_b128 v[106:109], v107 offset:14336
	s_waitcnt lgkmcnt(0)
	v_lshlrev_b32_e32 v246, 16, v194
	v_and_b32_e32 v247, 0xffff0000, v194
	v_lshlrev_b32_e32 v194, 16, v195
	v_and_b32_e32 v195, 0xffff0000, v195
	v_lshlrev_b32_e32 v248, 16, v196
	v_and_b32_e32 v249, 0xffff0000, v196
	v_lshlrev_b32_e32 v250, 16, v197
	v_and_b32_e32 v251, 0xffff0000, v197
	v_pk_add_f32 v[196:197], v[152:153], v[194:195]
	v_pk_add_f32 v[194:195], v[150:151], v[246:247]
	v_pk_add_f32 v[152:153], v[156:157], v[250:251]
	v_pk_add_f32 v[150:151], v[154:155], v[248:249]
	v_lshl_add_u64 v[156:157], v[232:233], 2, s[12:13]
	s_cbranch_vccnz .LBB0_1029
	s_mov_b64 s[8:9], 0
	global_store_dwordx4 v[156:157], v[194:197], off sc1
	global_store_dwordx4 v[156:157], v[150:153], off offset:16 sc1
